# seam 13-15 also a group barrier, guarded by a lagged all-workgroups-left-phase-12 counter (HFF lies over QX); seam 7-9 stays a grid barrier
# speedup vs baseline: 1.0093x; 1.0093x over previous
.LBB0_2496:
	s_cmp_gt_i32 s87, 13
	s_cselect_b64 s[2:3], -1, 0
	s_and_b64 s[0:1], s[0:1], s[2:3]
	s_andn2_b64 vcc, exec, s[0:1]
	s_cbranch_vccnz .LBB0_2550
	s_waitcnt vmcnt(0)
	s_waitcnt vmcnt(0)
	s_barrier
	s_mov_b64 s[0:1], exec
	v_readlane_b32 s4, v251, 1
	v_readlane_b32 s5, v251, 2
	s_and_b64 s[4:5], s[0:1], s[4:5]
	s_mov_b64 exec, s[4:5]
	s_cbranch_execz .LBB0_2549
	s_waitcnt vmcnt(0) expcnt(0) lgkmcnt(0)
	buffer_inv sc1
	s_and_b32 s4, s90, 7
	s_lshl_b32 s4, s4, 8
	s_add_i32 s4, s4, 0x3600
	v_mov_b32_e32 v0, s4
	v_mov_b32_e32 v2, 1
	v_mov_b32_e32 v1, 0x3e80
	global_atomic_add v1, v2, s[96:97]
	global_atomic_add v0, v0, v2, s[96:97] sc0
	s_nop 0
	v_mov_b32_e32 v2, 0x3e00
	global_load_dword v2, v2, s[96:97] sc1
	s_waitcnt vmcnt(0)
	v_readfirstlane_b32 s5, v2
	v_readfirstlane_b32 vcc_lo, v0
	s_cmp_lg_u32 s5, 0
	s_cbranch_scc1 .Lgb_orig1
	s_or_b32 s5, vcc_lo, 31
	s_cmp_eq_u32 s5, vcc_lo
	s_cbranch_scc1 .Lgb_done1
	s_add_i32 s5, s5, 1
	s_mov_b32 vcc_hi, 0
	v_mov_b32_e32 v0, s4

.LBB0_2589:
	s_cmp_lt_i32 s87, 15
	s_cselect_b64 s[2:3], -1, 0
	s_xor_b64 s[0:1], s[0:1], -1
	s_or_b64 s[0:1], s[0:1], s[2:3]
	s_and_b64 vcc, exec, s[0:1]
	s_cbranch_vccnz .LBB0_2643
	s_waitcnt vmcnt(0)
	s_waitcnt vmcnt(0)
	s_barrier
	s_mov_b64 s[0:1], exec
	v_readlane_b32 s2, v251, 1
	v_readlane_b32 s3, v251, 2
	s_and_b64 s[2:3], s[0:1], s[2:3]
	s_mov_b64 exec, s[2:3]
	s_cbranch_execz .LBB0_2642
	s_waitcnt vmcnt(0) expcnt(0) lgkmcnt(0)
	buffer_inv sc1
	s_and_b32 s2, s90, 7
	s_lshl_b32 s2, s2, 8
	s_add_i32 s2, s2, 0x3600
	v_mov_b32_e32 v0, s2
	v_mov_b32_e32 v2, 1
	global_atomic_add v0, v0, v2, s[96:97] sc0
	s_nop 0
	v_mov_b32_e32 v2, 0x3e00
	global_load_dword v2, v2, s[96:97] sc1
	v_mov_b32_e32 v1, 0x3e80
	global_load_dword v3, v1, s[96:97] sc1
	s_waitcnt vmcnt(0)
	v_readfirstlane_b32 s3, v2
	v_readfirstlane_b32 vcc_lo, v0
	s_cmp_lg_u32 s3, 0
	s_cbranch_scc1 .Lgb_orig2
	s_or_b32 s3, vcc_lo, 31
	s_cmp_eq_u32 s3, vcc_lo
	s_cbranch_scc1 .Lgb_done2
	s_add_i32 s3, s3, 1
	s_mov_b32 vcc_hi, 0
	v_mov_b32_e32 v0, s2

.Lgb_done2:
	s_mov_b32 vcc_hi, 0
.Lgb_lag2:
	v_readfirstlane_b32 vcc_lo, v3
	s_cmp_ge_u32 vcc_lo, 0x100
	s_cbranch_scc1 .Lgb_lagok2
	s_add_i32 vcc_hi, vcc_hi, 1
	s_cmp_lt_u32 vcc_hi, 0x40000
	s_cbranch_scc0 .Lgb_lagok2
	s_sleep 1
	global_load_dword v3, v1, s[96:97] sc1
	s_waitcnt vmcnt(0)
	s_branch .Lgb_lag2
